# pass2 d0 rewritten by hand: rank-1 state updates on v_mfma_f32_4x4x1_16b_f32 bursts, DPP dots, LDS-staged pattern operands
# speedup vs baseline: 1.0083x; 1.0083x over previous
; #define MKR(ptr) __builtin_amdgcn_make_buffer_rsrc((void*)(ptr), 0, 0x7fffffff, 0x00027000)
; __device__ __forceinline__ void scan_pass2(const Params& p, int d) {
;     const int lane = threadIdx.x & 63, wid = __builtin_amdgcn_readfirstlane(threadIdx.x >> 6); const unsigned lo16 = (lane & 15) * 16, lo2 = lane * 2, lo4b = lane * 4;
;     const float* Wd = (const float*)(p.ws + O_KD); const float* Bd = (const float*)(p.ws + O_Y); const u16* KB = (const u16*)(p.ws + O_K); const float* A = (const float*)(p.ws + O_A); const float* R = (const float*)(p.ws + O_R); const unsigned lo8 = (lane & 15) * 8;
;     const u16* V = (const u16*)(p.ws + O_V); const float* SIT = (const float*)(p.ws + O_SIT); float* Y = p.out;
;     for (int item = blockIdx.x * 8 + wid; item < 32 * NC; item += gridDim.x * 8) {
;         const int bh = item / NC, c = item - bh * NC, b = bh >> 4, h = bh & 15;
;         const int t0 = d ? (SEQ - 1 - c * LC) : c * LC;
;         const size_t off0 = ((size_t)(b * SEQ + t0)) * RW + h * 64; const long stp = d ? -(long)RW : (long)RW;
;         const unsigned ob4 = (unsigned)(off0 * 4), ob2 = (unsigned)(off0 * 2);
;         const __amdgpu_buffer_rsrc_t rW = MKR(Wd), rA = MKR(A), rB = MKR(Bd), rK = MKR(KB), rV = MKR(V), rR = MKR(R), rY = MKR(Y);
;         const f32x4 ka4 = *(const f32x4*)(p.k_a + h * 64 + (lane & 15) * 4), c04 = 1.0f - ka4;
;         float S[64];
;         if (c == 0) {
; #pragma unroll
;             for (int i = 0; i < 64; ++i) S[i] = 0.f;
;         } else { const float* si = SIT + ((size_t)(bh * NC + c)) * 4096 + lane * 64;
; #pragma unroll
;             for (int i = 0; i < 16; ++i) { const f32x4 q = *(const f32x4*)(si + 4 * i); S[4 * i] = q[0]; S[4 * i + 1] = q[1]; S[4 * i + 2] = q[2]; S[4 * i + 3] = q[3]; } }
;     ...
;         In2 i0, i1; LD2(i0, 0);
.LBB0_688:
	s_cmp_lt_i32 s58, 7
	s_cselect_b64 s[0:1], -1, 0
	s_cmp_gt_i32 s59, 6
	s_cselect_b64 s[4:5], -1, 0
	s_and_b64 s[0:1], s[0:1], s[4:5]
	s_andn2_b64 vcc, exec, s[0:1]
	s_cbranch_vccnz .LBB0_750
	v_readfirstlane_b32 s0, v254
	s_nop 3
	s_lshr_b32 s1, s0, 6
	s_lshl_b32 s0, s2, 3
	s_add_i32 s0, s1, s0
	s_mov_b32 s64, s56
	s_and_b32 s65, s57, 0xffff
	s_brev_b32 s66, -2
	s_mov_b32 s67, 0x27000
	s_mov_b32 s68, s54
	s_and_b32 s69, s55, 0xffff
	s_mov_b32 s70, s66
	s_mov_b32 s71, s67
	v_and_b32_e32 v172, 63, v254
	v_and_b32_e32 v173, 15, v254
	v_lshlrev_b32_e32 v164, 4, v173
	v_lshlrev_b32_e32 v165, 3, v173
	v_lshlrev_b32_e32 v166, 1, v172
	v_lshlrev_b32_e32 v167, 2, v172
	v_lshlrev_b32_e32 v170, 8, v172
	s_lshl_b32 s3, s1, 10
	s_add_u32 s3, s3, 0x10000
	v_add_u32_e32 v168, s3, v164
	v_and_b32_e32 v169, 3, v254
	v_lshlrev_b32_e32 v169, 2, v169
	v_add_u32_e32 v169, s3, v169
.Lmy_p2d0_item:
	s_cmpk_gt_i32 s0, 0x7ff
	s_cbranch_scc1 .Lmy_p2d0_end
	s_lshr_b32 s86, s0, 6
	s_and_b32 s85, s0, 63
	s_and_b32 s87, s86, 15
	s_lshr_b32 s6, s86, 4
	s_lshl_b32 s6, s6, 14
	s_lshl_b32 s7, s85, 8
	s_add_u32 s6, s6, s7
	s_lshl_b32 s6, s6, 10
	s_lshl_b32 s7, s87, 6
	s_add_u32 s84, s6, s7
	s_lshl_b32 s6, s84, 2
	s_lshl_b32 s7, s84, 1
	s_add_u32 s72, s6, 0xb800000
	s_add_u32 s73, s6, 0x24800000
	s_add_u32 s74, s6, 0x35a00000
	s_add_u32 s75, s6, 0x1c800000
	s_add_u32 s76, s7, 0x30800000
	s_add_u32 s77, s7, 0x2c800000
	s_mov_b32 s78, s6
	s_mov_b32 s79, s6
	s_mov_b32 s80, 0
	s_lshl_b32 s8, s87, 8
	s_add_u32 s4, s42, s8
	s_addc_u32 s5, s43, 0
	global_load_dwordx4 v[148:151], v164, s[4:5]
	buffer_load_dwordx4 v[96:99], v164, s[64:67], s72 offen
	buffer_load_dwordx4 v[100:103], v164, s[64:67], s73 offen
	buffer_load_dwordx4 v[104:107], v164, s[64:67], s74 offen
	buffer_load_dwordx4 v[108:111], v164, s[64:67], s75 offen
	buffer_load_dwordx2 v[112:113], v165, s[64:67], s76 offen
	buffer_load_ushort v114, v166, s[64:67], s77 offen
	s_add_u32 s72, s72, 0x1000
	s_add_u32 s73, s73, 0x1000
	s_add_u32 s74, s74, 0x1000
	s_add_u32 s75, s75, 0x1000
	s_add_u32 s78, s78, 0x1000
	s_add_u32 s76, s76, 0x800
	s_add_u32 s77, s77, 0x800
	s_mov_b32 s80, 1
	s_cmp_eq_u32 s85, 0
	s_cbranch_scc1 .Lmy_p2d0_zero
	s_lshl_b32 s8, s0, 14
	s_add_u32 s8, s8, 0x3da00000
	s_add_u32 s4, s56, s8
	s_addc_u32 s5, s57, 0
	global_load_dwordx4 v[0:3], v170, s[4:5] offset:0
	global_load_dwordx4 v[4:7], v170, s[4:5] offset:16
	global_load_dwordx4 v[8:11], v170, s[4:5] offset:32
	global_load_dwordx4 v[12:15], v170, s[4:5] offset:48
	global_load_dwordx4 v[16:19], v170, s[4:5] offset:64
	global_load_dwordx4 v[20:23], v170, s[4:5] offset:80
	global_load_dwordx4 v[24:27], v170, s[4:5] offset:96
	global_load_dwordx4 v[28:31], v170, s[4:5] offset:112
	global_load_dwordx4 v[32:35], v170, s[4:5] offset:128
	global_load_dwordx4 v[36:39], v170, s[4:5] offset:144
	global_load_dwordx4 v[40:43], v170, s[4:5] offset:160
	global_load_dwordx4 v[44:47], v170, s[4:5] offset:176
	global_load_dwordx4 v[48:51], v170, s[4:5] offset:192
	global_load_dwordx4 v[52:55], v170, s[4:5] offset:208
	global_load_dwordx4 v[56:59], v170, s[4:5] offset:224
	global_load_dwordx4 v[60:63], v170, s[4:5] offset:240
	s_branch .Lmy_p2d0_init_done
.Lmy_p2d0_zero:
	v_mov_b32_e32 v0, 0
	v_mov_b32_e32 v1, 0
	v_mov_b32_e32 v2, 0
	v_mov_b32_e32 v3, 0
	v_mov_b32_e32 v4, 0
	v_mov_b32_e32 v5, 0
	v_mov_b32_e32 v6, 0
	v_mov_b32_e32 v7, 0
	v_mov_b32_e32 v8, 0
	v_mov_b32_e32 v9, 0
	v_mov_b32_e32 v10, 0
	v_mov_b32_e32 v11, 0
	v_mov_b32_e32 v12, 0
	v_mov_b32_e32 v13, 0
	v_mov_b32_e32 v14, 0
	v_mov_b32_e32 v15, 0
	v_mov_b32_e32 v16, 0
	v_mov_b32_e32 v17, 0
	v_mov_b32_e32 v18, 0
	v_mov_b32_e32 v19, 0
	v_mov_b32_e32 v20, 0
	v_mov_b32_e32 v21, 0
	v_mov_b32_e32 v22, 0
	v_mov_b32_e32 v23, 0
	v_mov_b32_e32 v24, 0
	v_mov_b32_e32 v25, 0
	v_mov_b32_e32 v26, 0
	v_mov_b32_e32 v27, 0
	v_mov_b32_e32 v28, 0
	v_mov_b32_e32 v29, 0
	v_mov_b32_e32 v30, 0
	v_mov_b32_e32 v31, 0
	v_mov_b32_e32 v32, 0
	v_mov_b32_e32 v33, 0
	v_mov_b32_e32 v34, 0
	v_mov_b32_e32 v35, 0
	v_mov_b32_e32 v36, 0
	v_mov_b32_e32 v37, 0
	v_mov_b32_e32 v38, 0
	v_mov_b32_e32 v39, 0
	v_mov_b32_e32 v40, 0
	v_mov_b32_e32 v41, 0
	v_mov_b32_e32 v42, 0
	v_mov_b32_e32 v43, 0
	v_mov_b32_e32 v44, 0
	v_mov_b32_e32 v45, 0
	v_mov_b32_e32 v46, 0
	v_mov_b32_e32 v47, 0
	v_mov_b32_e32 v48, 0
	v_mov_b32_e32 v49, 0
	v_mov_b32_e32 v50, 0
	v_mov_b32_e32 v51, 0
	v_mov_b32_e32 v52, 0
	v_mov_b32_e32 v53, 0
	v_mov_b32_e32 v54, 0
	v_mov_b32_e32 v55, 0
	v_mov_b32_e32 v56, 0
	v_mov_b32_e32 v57, 0
	v_mov_b32_e32 v58, 0
	v_mov_b32_e32 v59, 0
	v_mov_b32_e32 v60, 0
	v_mov_b32_e32 v61, 0
	v_mov_b32_e32 v62, 0
	v_mov_b32_e32 v63, 0
.Lmy_p2d0_init_done:
	s_waitcnt vmcnt(0)
	v_sub_f32_e32 v152, 1.0, v148
	v_sub_f32_e32 v153, 1.0, v149
	v_sub_f32_e32 v154, 1.0, v150
	v_sub_f32_e32 v155, 1.0, v151
	s_movk_i32 s83, 128
;     static __device__ __forceinline__ void dot(const float (&S)[64], const f32x4& a, float (&s)[4]) {
;         if constexpr (K == 0) {
;             asm volatile("v_mul_f32_dpp %0, %4, %8 row_newbcast:%16" DPPM "v_mul_f32_dpp %1, %5, %9 row_newbcast:%16" DPPM "v_mul_f32_dpp %2, %6, %10 row_newbcast:%16" DPPM "v_mul_f32_dpp %3, %7, %11 row_newbcast:%16" DPPM
;                          "v_fmac_f32_dpp %0, %4, %12 row_newbcast:%17" DPPM "v_fmac_f32_dpp %1, %5, %13 row_newbcast:%17" DPPM "v_fmac_f32_dpp %2, %6, %14 row_newbcast:%17" DPPM "v_fmac_f32_dpp %3, %7, %15 row_newbcast:%17" DPPM
;                          : "=&v"(s[0]), "=&v"(s[1]), "=&v"(s[2]), "=&v"(s[3])
;                          : "v"(a[0]), "v"(a[1]), "v"(a[2]), "v"(a[3]), "v"(S[K]), "v"(S[K + 1]), "v"(S[K + 2]), "v"(S[K + 3]), "v"(S[K + 4]), "v"(S[K + 5]), "v"(S[K + 6]), "v"(S[K + 7]), "n"(N0), "n"(N1));
;         } else
;         asm volatile("v_fmac_f32_dpp %0, %4, %8 row_newbcast:%16" DPPM "v_fmac_f32_dpp %1, %5, %9 row_newbcast:%16" DPPM "v_fmac_f32_dpp %2, %6, %10 row_newbcast:%16" DPPM "v_fmac_f32_dpp %3, %7, %11 row_newbcast:%16" DPPM
;                      "v_fmac_f32_dpp %0, %4, %12 row_newbcast:%17" DPPM "v_fmac_f32_dpp %1, %5, %13 row_newbcast:%17" DPPM "v_fmac_f32_dpp %2, %6, %14 row_newbcast:%17" DPPM "v_fmac_f32_dpp %3, %7, %15 row_newbcast:%17" DPPM
;                      : "+v"(s[0]), "+v"(s[1]), "+v"(s[2]), "+v"(s[3])
;                      : "v"(a[0]), "v"(a[1]), "v"(a[2]), "v"(a[3]), "v"(S[K]), "v"(S[K + 1]), "v"(S[K + 2]), "v"(S[K + 3]), "v"(S[K + 4]), "v"(S[K + 5]), "v"(S[K + 6]), "v"(S[K + 7]), "n"(N0), "n"(N1));
;         if constexpr (K + 8 < 64) ScanK<K + 8>::dot(S, a, s);
;     }
;     static __device__ __forceinline__ void upd(float (&S)[64], const In2& in, float sa, float vv, float& y0, float& y1) {
;         float t0, t1, t2, t3;
;         asm volatile("v_mul_f32_dpp %0, %10, %27 row_newbcast:%28" DPPM "v_mul_f32_dpp %1, %11, %27 row_newbcast:%28" DPPM "v_mul_f32_dpp %2, %12, %27 row_newbcast:%28" DPPM "v_mul_f32_dpp %3, %13, %27 row_newbcast:%28" DPPM
;                      "v_fmac_f32_dpp %0, %14, %6 row_newbcast:%28" DPPM "v_fmac_f32_dpp %1, %15, %7 row_newbcast:%28" DPPM "v_fmac_f32_dpp %2, %16, %8 row_newbcast:%28" DPPM "v_fmac_f32_dpp %3, %17, %9 row_newbcast:%28" DPPM
.Lmy_p2d0_loop:
	s_waitcnt vmcnt(0)
	buffer_load_dwordx4 v[116:119], v164, s[64:67], s72 offen
	buffer_load_dwordx4 v[120:123], v164, s[64:67], s73 offen
	buffer_load_dwordx4 v[124:127], v164, s[64:67], s74 offen
	buffer_load_dwordx4 v[128:131], v164, s[64:67], s75 offen
	buffer_load_dwordx2 v[132:133], v165, s[64:67], s76 offen
	buffer_load_ushort v134, v166, s[64:67], s77 offen
	s_cmp_lt_u32 s80, 255
	s_cselect_b32 s81, 0x1000, 0
	s_cselect_b32 s82, 0x800, 0
	s_cselect_b32 s9, 1, 0
	s_add_u32 s80, s80, s9
	s_add_u32 s72, s72, s81
	s_add_u32 s73, s73, s81
	s_add_u32 s74, s74, s81
	s_add_u32 s75, s75, s81
	s_add_u32 s78, s78, s81
	s_add_u32 s76, s76, s82
	s_add_u32 s77, s77, s82
	v_pk_fma_f32 v[144:145], v[104:105], v[148:149], v[152:153]
	v_pk_fma_f32 v[146:147], v[106:107], v[150:151], v[154:155]
	v_pk_mul_f32 v[136:137], v[100:101], v[104:105]
	v_pk_mul_f32 v[138:139], v[102:103], v[106:107]
	v_lshlrev_b32_e32 v140, 16, v112
	v_and_b32_e32 v141, 0xffff0000, v112
	v_lshlrev_b32_e32 v142, 16, v113
	v_and_b32_e32 v143, 0xffff0000, v113
	v_pk_mul_f32 v[140:141], v[140:141], v[144:145]
	v_pk_mul_f32 v[142:143], v[142:143], v[146:147]
	v_lshlrev_b32_e32 v163, 16, v114
	ds_write_b128 v168, v[136:139]
	ds_write_b128 v168, v[140:143] offset:256
	ds_read2_b32 v[64:65], v169 offset0:0 offset1:4
	ds_read2_b32 v[66:67], v169 offset0:8 offset1:12
	ds_read2_b32 v[68:69], v169 offset0:16 offset1:20
	ds_read2_b32 v[70:71], v169 offset0:24 offset1:28
	ds_read2_b32 v[72:73], v169 offset0:32 offset1:36
	ds_read2_b32 v[74:75], v169 offset0:40 offset1:44
	ds_read2_b32 v[76:77], v169 offset0:48 offset1:52
	ds_read2_b32 v[78:79], v169 offset0:56 offset1:60
	ds_read2_b32 v[80:81], v169 offset0:64 offset1:68
	ds_read2_b32 v[82:83], v169 offset0:72 offset1:76
	ds_read2_b32 v[84:85], v169 offset0:80 offset1:84
	ds_read2_b32 v[86:87], v169 offset0:88 offset1:92
	ds_read2_b32 v[88:89], v169 offset0:96 offset1:100
	ds_read2_b32 v[90:91], v169 offset0:104 offset1:108
	ds_read2_b32 v[92:93], v169 offset0:112 offset1:116
	ds_read2_b32 v[94:95], v169 offset0:120 offset1:124
	v_mul_f32_dpp v156, v100, v0 row_newbcast:0 row_mask:0xf bank_mask:0xf
	v_mul_f32_dpp v0, v96, v0 row_newbcast:0 row_mask:0xf bank_mask:0xf
	v_mul_f32_dpp v157, v101, v1 row_newbcast:0 row_mask:0xf bank_mask:0xf
	v_mul_f32_dpp v1, v97, v1 row_newbcast:0 row_mask:0xf bank_mask:0xf
	v_mul_f32_dpp v158, v102, v2 row_newbcast:0 row_mask:0xf bank_mask:0xf
	v_mul_f32_dpp v2, v98, v2 row_newbcast:0 row_mask:0xf bank_mask:0xf
	v_mul_f32_dpp v159, v103, v3 row_newbcast:0 row_mask:0xf bank_mask:0xf
	v_mul_f32_dpp v3, v99, v3 row_newbcast:0 row_mask:0xf bank_mask:0xf
	v_fmac_f32_dpp v156, v100, v4 row_newbcast:1 row_mask:0xf bank_mask:0xf
	v_mul_f32_dpp v4, v96, v4 row_newbcast:1 row_mask:0xf bank_mask:0xf
	v_fmac_f32_dpp v157, v101, v5 row_newbcast:1 row_mask:0xf bank_mask:0xf
	v_mul_f32_dpp v5, v97, v5 row_newbcast:1 row_mask:0xf bank_mask:0xf
	v_fmac_f32_dpp v158, v102, v6 row_newbcast:1 row_mask:0xf bank_mask:0xf
	v_mul_f32_dpp v6, v98, v6 row_newbcast:1 row_mask:0xf bank_mask:0xf
	v_fmac_f32_dpp v159, v103, v7 row_newbcast:1 row_mask:0xf bank_mask:0xf
	v_mul_f32_dpp v7, v99, v7 row_newbcast:1 row_mask:0xf bank_mask:0xf
	v_fmac_f32_dpp v156, v100, v8 row_newbcast:2 row_mask:0xf bank_mask:0xf
	v_mul_f32_dpp v8, v96, v8 row_newbcast:2 row_mask:0xf bank_mask:0xf
	v_fmac_f32_dpp v157, v101, v9 row_newbcast:2 row_mask:0xf bank_mask:0xf
	v_mul_f32_dpp v9, v97, v9 row_newbcast:2 row_mask:0xf bank_mask:0xf
	v_fmac_f32_dpp v158, v102, v10 row_newbcast:2 row_mask:0xf bank_mask:0xf
	v_mul_f32_dpp v10, v98, v10 row_newbcast:2 row_mask:0xf bank_mask:0xf
	v_fmac_f32_dpp v159, v103, v11 row_newbcast:2 row_mask:0xf bank_mask:0xf
	v_mul_f32_dpp v11, v99, v11 row_newbcast:2 row_mask:0xf bank_mask:0xf
	v_fmac_f32_dpp v156, v100, v12 row_newbcast:3 row_mask:0xf bank_mask:0xf
	v_mul_f32_dpp v12, v96, v12 row_newbcast:3 row_mask:0xf bank_mask:0xf
	v_fmac_f32_dpp v157, v101, v13 row_newbcast:3 row_mask:0xf bank_mask:0xf
	v_mul_f32_dpp v13, v97, v13 row_newbcast:3 row_mask:0xf bank_mask:0xf
	v_fmac_f32_dpp v158, v102, v14 row_newbcast:3 row_mask:0xf bank_mask:0xf
	v_mul_f32_dpp v14, v98, v14 row_newbcast:3 row_mask:0xf bank_mask:0xf
	v_fmac_f32_dpp v159, v103, v15 row_newbcast:3 row_mask:0xf bank_mask:0xf
	v_mul_f32_dpp v15, v99, v15 row_newbcast:3 row_mask:0xf bank_mask:0xf
	v_fmac_f32_dpp v156, v100, v16 row_newbcast:4 row_mask:0xf bank_mask:0xf
	v_mul_f32_dpp v16, v96, v16 row_newbcast:4 row_mask:0xf bank_mask:0xf
	v_fmac_f32_dpp v157, v101, v17 row_newbcast:4 row_mask:0xf bank_mask:0xf
	v_mul_f32_dpp v17, v97, v17 row_newbcast:4 row_mask:0xf bank_mask:0xf
	v_fmac_f32_dpp v158, v102, v18 row_newbcast:4 row_mask:0xf bank_mask:0xf
	v_mul_f32_dpp v18, v98, v18 row_newbcast:4 row_mask:0xf bank_mask:0xf
	v_fmac_f32_dpp v159, v103, v19 row_newbcast:4 row_mask:0xf bank_mask:0xf
	v_mul_f32_dpp v19, v99, v19 row_newbcast:4 row_mask:0xf bank_mask:0xf
	v_fmac_f32_dpp v156, v100, v20 row_newbcast:5 row_mask:0xf bank_mask:0xf
	v_mul_f32_dpp v20, v96, v20 row_newbcast:5 row_mask:0xf bank_mask:0xf
	v_fmac_f32_dpp v157, v101, v21 row_newbcast:5 row_mask:0xf bank_mask:0xf
	v_mul_f32_dpp v21, v97, v21 row_newbcast:5 row_mask:0xf bank_mask:0xf
	v_fmac_f32_dpp v158, v102, v22 row_newbcast:5 row_mask:0xf bank_mask:0xf
	v_mul_f32_dpp v22, v98, v22 row_newbcast:5 row_mask:0xf bank_mask:0xf
	v_fmac_f32_dpp v159, v103, v23 row_newbcast:5 row_mask:0xf bank_mask:0xf
	v_mul_f32_dpp v23, v99, v23 row_newbcast:5 row_mask:0xf bank_mask:0xf
	v_fmac_f32_dpp v156, v100, v24 row_newbcast:6 row_mask:0xf bank_mask:0xf
	v_mul_f32_dpp v24, v96, v24 row_newbcast:6 row_mask:0xf bank_mask:0xf
;     static __device__ __forceinline__ void dot(const float (&S)[64], const f32x4& a, float (&s)[4]) {
;         if constexpr (K == 0) {
;             asm volatile("v_mul_f32_dpp %0, %4, %8 row_newbcast:%16" DPPM "v_mul_f32_dpp %1, %5, %9 row_newbcast:%16" DPPM "v_mul_f32_dpp %2, %6, %10 row_newbcast:%16" DPPM "v_mul_f32_dpp %3, %7, %11 row_newbcast:%16" DPPM
;                          "v_fmac_f32_dpp %0, %4, %12 row_newbcast:%17" DPPM "v_fmac_f32_dpp %1, %5, %13 row_newbcast:%17" DPPM "v_fmac_f32_dpp %2, %6, %14 row_newbcast:%17" DPPM "v_fmac_f32_dpp %3, %7, %15 row_newbcast:%17" DPPM
;                          : "=&v"(s[0]), "=&v"(s[1]), "=&v"(s[2]), "=&v"(s[3])
;                          : "v"(a[0]), "v"(a[1]), "v"(a[2]), "v"(a[3]), "v"(S[K]), "v"(S[K + 1]), "v"(S[K + 2]), "v"(S[K + 3]), "v"(S[K + 4]), "v"(S[K + 5]), "v"(S[K + 6]), "v"(S[K + 7]), "n"(N0), "n"(N1));
;         } else
;         asm volatile("v_fmac_f32_dpp %0, %4, %8 row_newbcast:%16" DPPM "v_fmac_f32_dpp %1, %5, %9 row_newbcast:%16" DPPM "v_fmac_f32_dpp %2, %6, %10 row_newbcast:%16" DPPM "v_fmac_f32_dpp %3, %7, %11 row_newbcast:%16" DPPM
;                      "v_fmac_f32_dpp %0, %4, %12 row_newbcast:%17" DPPM "v_fmac_f32_dpp %1, %5, %13 row_newbcast:%17" DPPM "v_fmac_f32_dpp %2, %6, %14 row_newbcast:%17" DPPM "v_fmac_f32_dpp %3, %7, %15 row_newbcast:%17" DPPM
;                      : "+v"(s[0]), "+v"(s[1]), "+v"(s[2]), "+v"(s[3])
;                      : "v"(a[0]), "v"(a[1]), "v"(a[2]), "v"(a[3]), "v"(S[K]), "v"(S[K + 1]), "v"(S[K + 2]), "v"(S[K + 3]), "v"(S[K + 4]), "v"(S[K + 5]), "v"(S[K + 6]), "v"(S[K + 7]), "n"(N0), "n"(N1));
;         if constexpr (K + 8 < 64) ScanK<K + 8>::dot(S, a, s);
;     }
	v_fmac_f32_dpp v157, v101, v25 row_newbcast:6 row_mask:0xf bank_mask:0xf
	v_mul_f32_dpp v25, v97, v25 row_newbcast:6 row_mask:0xf bank_mask:0xf
	v_fmac_f32_dpp v158, v102, v26 row_newbcast:6 row_mask:0xf bank_mask:0xf
	v_mul_f32_dpp v26, v98, v26 row_newbcast:6 row_mask:0xf bank_mask:0xf
	v_fmac_f32_dpp v159, v103, v27 row_newbcast:6 row_mask:0xf bank_mask:0xf
	v_mul_f32_dpp v27, v99, v27 row_newbcast:6 row_mask:0xf bank_mask:0xf
	v_fmac_f32_dpp v156, v100, v28 row_newbcast:7 row_mask:0xf bank_mask:0xf
	v_mul_f32_dpp v28, v96, v28 row_newbcast:7 row_mask:0xf bank_mask:0xf
	v_fmac_f32_dpp v157, v101, v29 row_newbcast:7 row_mask:0xf bank_mask:0xf
	v_mul_f32_dpp v29, v97, v29 row_newbcast:7 row_mask:0xf bank_mask:0xf
	v_fmac_f32_dpp v158, v102, v30 row_newbcast:7 row_mask:0xf bank_mask:0xf
	v_mul_f32_dpp v30, v98, v30 row_newbcast:7 row_mask:0xf bank_mask:0xf
	v_fmac_f32_dpp v159, v103, v31 row_newbcast:7 row_mask:0xf bank_mask:0xf
	v_mul_f32_dpp v31, v99, v31 row_newbcast:7 row_mask:0xf bank_mask:0xf
	v_fmac_f32_dpp v156, v100, v32 row_newbcast:8 row_mask:0xf bank_mask:0xf
	v_mul_f32_dpp v32, v96, v32 row_newbcast:8 row_mask:0xf bank_mask:0xf
	v_fmac_f32_dpp v157, v101, v33 row_newbcast:8 row_mask:0xf bank_mask:0xf
	v_mul_f32_dpp v33, v97, v33 row_newbcast:8 row_mask:0xf bank_mask:0xf
	v_fmac_f32_dpp v158, v102, v34 row_newbcast:8 row_mask:0xf bank_mask:0xf
	v_mul_f32_dpp v34, v98, v34 row_newbcast:8 row_mask:0xf bank_mask:0xf
	v_fmac_f32_dpp v159, v103, v35 row_newbcast:8 row_mask:0xf bank_mask:0xf
	v_mul_f32_dpp v35, v99, v35 row_newbcast:8 row_mask:0xf bank_mask:0xf
	v_fmac_f32_dpp v156, v100, v36 row_newbcast:9 row_mask:0xf bank_mask:0xf
	v_mul_f32_dpp v36, v96, v36 row_newbcast:9 row_mask:0xf bank_mask:0xf
	v_fmac_f32_dpp v157, v101, v37 row_newbcast:9 row_mask:0xf bank_mask:0xf
	v_mul_f32_dpp v37, v97, v37 row_newbcast:9 row_mask:0xf bank_mask:0xf
	v_fmac_f32_dpp v158, v102, v38 row_newbcast:9 row_mask:0xf bank_mask:0xf
	v_mul_f32_dpp v38, v98, v38 row_newbcast:9 row_mask:0xf bank_mask:0xf
	v_fmac_f32_dpp v159, v103, v39 row_newbcast:9 row_mask:0xf bank_mask:0xf
	v_mul_f32_dpp v39, v99, v39 row_newbcast:9 row_mask:0xf bank_mask:0xf
	v_fmac_f32_dpp v156, v100, v40 row_newbcast:10 row_mask:0xf bank_mask:0xf
	v_mul_f32_dpp v40, v96, v40 row_newbcast:10 row_mask:0xf bank_mask:0xf
	v_fmac_f32_dpp v157, v101, v41 row_newbcast:10 row_mask:0xf bank_mask:0xf
	v_mul_f32_dpp v41, v97, v41 row_newbcast:10 row_mask:0xf bank_mask:0xf
	v_fmac_f32_dpp v158, v102, v42 row_newbcast:10 row_mask:0xf bank_mask:0xf
	v_mul_f32_dpp v42, v98, v42 row_newbcast:10 row_mask:0xf bank_mask:0xf
	v_fmac_f32_dpp v159, v103, v43 row_newbcast:10 row_mask:0xf bank_mask:0xf
	v_mul_f32_dpp v43, v99, v43 row_newbcast:10 row_mask:0xf bank_mask:0xf
	v_fmac_f32_dpp v156, v100, v44 row_newbcast:11 row_mask:0xf bank_mask:0xf
	v_mul_f32_dpp v44, v96, v44 row_newbcast:11 row_mask:0xf bank_mask:0xf
	v_fmac_f32_dpp v157, v101, v45 row_newbcast:11 row_mask:0xf bank_mask:0xf
	v_mul_f32_dpp v45, v97, v45 row_newbcast:11 row_mask:0xf bank_mask:0xf
	v_fmac_f32_dpp v158, v102, v46 row_newbcast:11 row_mask:0xf bank_mask:0xf
	v_mul_f32_dpp v46, v98, v46 row_newbcast:11 row_mask:0xf bank_mask:0xf
	v_fmac_f32_dpp v159, v103, v47 row_newbcast:11 row_mask:0xf bank_mask:0xf
	v_mul_f32_dpp v47, v99, v47 row_newbcast:11 row_mask:0xf bank_mask:0xf
	v_fmac_f32_dpp v156, v100, v48 row_newbcast:12 row_mask:0xf bank_mask:0xf
	v_mul_f32_dpp v48, v96, v48 row_newbcast:12 row_mask:0xf bank_mask:0xf
	v_fmac_f32_dpp v157, v101, v49 row_newbcast:12 row_mask:0xf bank_mask:0xf
	v_mul_f32_dpp v49, v97, v49 row_newbcast:12 row_mask:0xf bank_mask:0xf
	v_fmac_f32_dpp v158, v102, v50 row_newbcast:12 row_mask:0xf bank_mask:0xf
	v_mul_f32_dpp v50, v98, v50 row_newbcast:12 row_mask:0xf bank_mask:0xf
	v_fmac_f32_dpp v159, v103, v51 row_newbcast:12 row_mask:0xf bank_mask:0xf
	v_mul_f32_dpp v51, v99, v51 row_newbcast:12 row_mask:0xf bank_mask:0xf
	v_fmac_f32_dpp v156, v100, v52 row_newbcast:13 row_mask:0xf bank_mask:0xf
	v_mul_f32_dpp v52, v96, v52 row_newbcast:13 row_mask:0xf bank_mask:0xf
	v_fmac_f32_dpp v157, v101, v53 row_newbcast:13 row_mask:0xf bank_mask:0xf
	v_mul_f32_dpp v53, v97, v53 row_newbcast:13 row_mask:0xf bank_mask:0xf
	v_fmac_f32_dpp v158, v102, v54 row_newbcast:13 row_mask:0xf bank_mask:0xf
	v_mul_f32_dpp v54, v98, v54 row_newbcast:13 row_mask:0xf bank_mask:0xf
	v_fmac_f32_dpp v159, v103, v55 row_newbcast:13 row_mask:0xf bank_mask:0xf
	v_mul_f32_dpp v55, v99, v55 row_newbcast:13 row_mask:0xf bank_mask:0xf
	v_fmac_f32_dpp v156, v100, v56 row_newbcast:14 row_mask:0xf bank_mask:0xf
	v_mul_f32_dpp v56, v96, v56 row_newbcast:14 row_mask:0xf bank_mask:0xf
	v_fmac_f32_dpp v157, v101, v57 row_newbcast:14 row_mask:0xf bank_mask:0xf
	v_mul_f32_dpp v57, v97, v57 row_newbcast:14 row_mask:0xf bank_mask:0xf
	v_fmac_f32_dpp v158, v102, v58 row_newbcast:14 row_mask:0xf bank_mask:0xf
	v_mul_f32_dpp v58, v98, v58 row_newbcast:14 row_mask:0xf bank_mask:0xf
	v_fmac_f32_dpp v159, v103, v59 row_newbcast:14 row_mask:0xf bank_mask:0xf
	v_mul_f32_dpp v59, v99, v59 row_newbcast:14 row_mask:0xf bank_mask:0xf
	v_fmac_f32_dpp v156, v100, v60 row_newbcast:15 row_mask:0xf bank_mask:0xf
	v_mul_f32_dpp v60, v96, v60 row_newbcast:15 row_mask:0xf bank_mask:0xf
	v_fmac_f32_dpp v157, v101, v61 row_newbcast:15 row_mask:0xf bank_mask:0xf
	v_mul_f32_dpp v61, v97, v61 row_newbcast:15 row_mask:0xf bank_mask:0xf
	v_fmac_f32_dpp v158, v102, v62 row_newbcast:15 row_mask:0xf bank_mask:0xf
	v_mul_f32_dpp v62, v98, v62 row_newbcast:15 row_mask:0xf bank_mask:0xf
	v_fmac_f32_dpp v159, v103, v63 row_newbcast:15 row_mask:0xf bank_mask:0xf
	v_mul_f32_dpp v63, v99, v63 row_newbcast:15 row_mask:0xf bank_mask:0xf
	v_add_f32_e32 v156, v156, v157
	v_add_f32_e32 v158, v158, v159
	v_add_f32_e32 v156, v156, v158
	v_xor_b32_e32 v162, 0x80000000, v156
	s_waitcnt lgkmcnt(0)
;     static __device__ __forceinline__ void upd(float (&S)[64], const In2& in, float sa, float vv, float& y0, float& y1) {
;         float t0, t1, t2, t3;
;         asm volatile("v_mul_f32_dpp %0, %10, %27 row_newbcast:%28" DPPM "v_mul_f32_dpp %1, %11, %27 row_newbcast:%28" DPPM "v_mul_f32_dpp %2, %12, %27 row_newbcast:%28" DPPM "v_mul_f32_dpp %3, %13, %27 row_newbcast:%28" DPPM
;                      "v_fmac_f32_dpp %0, %14, %6 row_newbcast:%28" DPPM "v_fmac_f32_dpp %1, %15, %7 row_newbcast:%28" DPPM "v_fmac_f32_dpp %2, %16, %8 row_newbcast:%28" DPPM "v_fmac_f32_dpp %3, %17, %9 row_newbcast:%28" DPPM
;                      "v_fmac_f32_dpp %0, %18, %26 row_newbcast:%28" DPPM "v_fmac_f32_dpp %1, %19, %26 row_newbcast:%28" DPPM "v_fmac_f32_dpp %2, %20, %26 row_newbcast:%28" DPPM "v_fmac_f32_dpp %3, %21, %26 row_newbcast:%28" DPPM
;                      "v_fmac_f32_dpp %4, %22, %0 row_newbcast:%28" DPPM "v_fmac_f32_dpp %5, %23, %1 row_newbcast:%28" DPPM "v_fmac_f32_dpp %4, %24, %2 row_newbcast:%28" DPPM "v_fmac_f32_dpp %5, %25, %3 row_newbcast:%28" DPPM
;                      : "=&v"(t0), "=&v"(t1), "=&v"(t2), "=&v"(t3), "+v"(y0), "+v"(y1)
;                      : "v"(S[K]), "v"(S[K + 1]), "v"(S[K + 2]), "v"(S[K + 3]), "v"(in.kd[0]), "v"(in.kd[1]), "v"(in.kd[2]), "v"(in.kd[3]), "v"(in.w[0]), "v"(in.w[1]), "v"(in.w[2]), "v"(in.w[3]),
;                        "v"(in.b[0]), "v"(in.b[1]), "v"(in.b[2]), "v"(in.b[3]), "v"(in.r[0]), "v"(in.r[1]), "v"(in.r[2]), "v"(in.r[3]), "v"(sa), "v"(vv), "n"(N0));
;         S[K] = t0; S[K + 1] = t1; S[K + 2] = t2; S[K + 3] = t3;
;         if constexpr (K + 4 < 64) ScanK<K + 4>::upd(S, in, sa, vv, y0, y1);
	s_nop 1
	v_mfma_f32_4x4x1_16b_f32 v[0:3], v64, v162, v[0:3]
	v_mfma_f32_4x4x1_16b_f32 v[4:7], v65, v162, v[4:7]
	v_mfma_f32_4x4x1_16b_f32 v[8:11], v66, v162, v[8:11]
	v_mfma_f32_4x4x1_16b_f32 v[12:15], v67, v162, v[12:15]
	v_mfma_f32_4x4x1_16b_f32 v[16:19], v68, v162, v[16:19]
	v_mfma_f32_4x4x1_16b_f32 v[20:23], v69, v162, v[20:23]
	v_mfma_f32_4x4x1_16b_f32 v[24:27], v70, v162, v[24:27]
	v_mfma_f32_4x4x1_16b_f32 v[28:31], v71, v162, v[28:31]
	v_mfma_f32_4x4x1_16b_f32 v[32:35], v72, v162, v[32:35]
	v_mfma_f32_4x4x1_16b_f32 v[36:39], v73, v162, v[36:39]
	v_mfma_f32_4x4x1_16b_f32 v[40:43], v74, v162, v[40:43]
	v_mfma_f32_4x4x1_16b_f32 v[44:47], v75, v162, v[44:47]
	v_mfma_f32_4x4x1_16b_f32 v[48:51], v76, v162, v[48:51]
	v_mfma_f32_4x4x1_16b_f32 v[52:55], v77, v162, v[52:55]
	v_mfma_f32_4x4x1_16b_f32 v[56:59], v78, v162, v[56:59]
	v_mfma_f32_4x4x1_16b_f32 v[60:63], v79, v162, v[60:63]
	v_mfma_f32_4x4x1_16b_f32 v[0:3], v80, v163, v[0:3]
	v_mfma_f32_4x4x1_16b_f32 v[4:7], v81, v163, v[4:7]
	v_mfma_f32_4x4x1_16b_f32 v[8:11], v82, v163, v[8:11]
	v_mfma_f32_4x4x1_16b_f32 v[12:15], v83, v163, v[12:15]
	v_mfma_f32_4x4x1_16b_f32 v[16:19], v84, v163, v[16:19]
	v_mfma_f32_4x4x1_16b_f32 v[20:23], v85, v163, v[20:23]
	v_mfma_f32_4x4x1_16b_f32 v[24:27], v86, v163, v[24:27]
	v_mfma_f32_4x4x1_16b_f32 v[28:31], v87, v163, v[28:31]
	v_mfma_f32_4x4x1_16b_f32 v[32:35], v88, v163, v[32:35]
	v_mfma_f32_4x4x1_16b_f32 v[36:39], v89, v163, v[36:39]
	v_mfma_f32_4x4x1_16b_f32 v[40:43], v90, v163, v[40:43]
	v_mfma_f32_4x4x1_16b_f32 v[44:47], v91, v163, v[44:47]
	v_mfma_f32_4x4x1_16b_f32 v[48:51], v92, v163, v[48:51]
	v_mfma_f32_4x4x1_16b_f32 v[52:55], v93, v163, v[52:55]
	v_mfma_f32_4x4x1_16b_f32 v[56:59], v94, v163, v[56:59]
	v_mfma_f32_4x4x1_16b_f32 v[60:63], v95, v163, v[60:63]
	v_mul_f32_dpp v160, v108, v0 row_newbcast:0 row_mask:0xf bank_mask:0xf
	v_mul_f32_dpp v161, v109, v1 row_newbcast:0 row_mask:0xf bank_mask:0xf
	v_fmac_f32_dpp v160, v110, v2 row_newbcast:0 row_mask:0xf bank_mask:0xf
	v_fmac_f32_dpp v161, v111, v3 row_newbcast:0 row_mask:0xf bank_mask:0xf
	v_fmac_f32_dpp v160, v108, v4 row_newbcast:1 row_mask:0xf bank_mask:0xf
	v_fmac_f32_dpp v161, v109, v5 row_newbcast:1 row_mask:0xf bank_mask:0xf
	v_fmac_f32_dpp v160, v110, v6 row_newbcast:1 row_mask:0xf bank_mask:0xf
	v_fmac_f32_dpp v161, v111, v7 row_newbcast:1 row_mask:0xf bank_mask:0xf
	v_fmac_f32_dpp v160, v108, v8 row_newbcast:2 row_mask:0xf bank_mask:0xf
	v_fmac_f32_dpp v161, v109, v9 row_newbcast:2 row_mask:0xf bank_mask:0xf
	v_fmac_f32_dpp v160, v110, v10 row_newbcast:2 row_mask:0xf bank_mask:0xf
	v_fmac_f32_dpp v161, v111, v11 row_newbcast:2 row_mask:0xf bank_mask:0xf
	v_fmac_f32_dpp v160, v108, v12 row_newbcast:3 row_mask:0xf bank_mask:0xf
	v_fmac_f32_dpp v161, v109, v13 row_newbcast:3 row_mask:0xf bank_mask:0xf
	v_fmac_f32_dpp v160, v110, v14 row_newbcast:3 row_mask:0xf bank_mask:0xf
	v_fmac_f32_dpp v161, v111, v15 row_newbcast:3 row_mask:0xf bank_mask:0xf
	v_fmac_f32_dpp v160, v108, v16 row_newbcast:4 row_mask:0xf bank_mask:0xf
	v_fmac_f32_dpp v161, v109, v17 row_newbcast:4 row_mask:0xf bank_mask:0xf
	v_fmac_f32_dpp v160, v110, v18 row_newbcast:4 row_mask:0xf bank_mask:0xf
	v_fmac_f32_dpp v161, v111, v19 row_newbcast:4 row_mask:0xf bank_mask:0xf
	v_fmac_f32_dpp v160, v108, v20 row_newbcast:5 row_mask:0xf bank_mask:0xf
	v_fmac_f32_dpp v161, v109, v21 row_newbcast:5 row_mask:0xf bank_mask:0xf
	v_fmac_f32_dpp v160, v110, v22 row_newbcast:5 row_mask:0xf bank_mask:0xf
	v_fmac_f32_dpp v161, v111, v23 row_newbcast:5 row_mask:0xf bank_mask:0xf
	v_fmac_f32_dpp v160, v108, v24 row_newbcast:6 row_mask:0xf bank_mask:0xf
	v_fmac_f32_dpp v161, v109, v25 row_newbcast:6 row_mask:0xf bank_mask:0xf
	v_fmac_f32_dpp v160, v110, v26 row_newbcast:6 row_mask:0xf bank_mask:0xf
	v_fmac_f32_dpp v161, v111, v27 row_newbcast:6 row_mask:0xf bank_mask:0xf
	v_fmac_f32_dpp v160, v108, v28 row_newbcast:7 row_mask:0xf bank_mask:0xf
	v_fmac_f32_dpp v161, v109, v29 row_newbcast:7 row_mask:0xf bank_mask:0xf
	v_fmac_f32_dpp v160, v110, v30 row_newbcast:7 row_mask:0xf bank_mask:0xf
	v_fmac_f32_dpp v161, v111, v31 row_newbcast:7 row_mask:0xf bank_mask:0xf
	v_fmac_f32_dpp v160, v108, v32 row_newbcast:8 row_mask:0xf bank_mask:0xf
	v_fmac_f32_dpp v161, v109, v33 row_newbcast:8 row_mask:0xf bank_mask:0xf
	v_fmac_f32_dpp v160, v110, v34 row_newbcast:8 row_mask:0xf bank_mask:0xf
	v_fmac_f32_dpp v161, v111, v35 row_newbcast:8 row_mask:0xf bank_mask:0xf
	v_fmac_f32_dpp v160, v108, v36 row_newbcast:9 row_mask:0xf bank_mask:0xf
	v_fmac_f32_dpp v161, v109, v37 row_newbcast:9 row_mask:0xf bank_mask:0xf
	v_fmac_f32_dpp v160, v110, v38 row_newbcast:9 row_mask:0xf bank_mask:0xf
	v_fmac_f32_dpp v161, v111, v39 row_newbcast:9 row_mask:0xf bank_mask:0xf
	v_fmac_f32_dpp v160, v108, v40 row_newbcast:10 row_mask:0xf bank_mask:0xf
	v_fmac_f32_dpp v161, v109, v41 row_newbcast:10 row_mask:0xf bank_mask:0xf
	v_fmac_f32_dpp v160, v110, v42 row_newbcast:10 row_mask:0xf bank_mask:0xf
	v_fmac_f32_dpp v161, v111, v43 row_newbcast:10 row_mask:0xf bank_mask:0xf
	v_fmac_f32_dpp v160, v108, v44 row_newbcast:11 row_mask:0xf bank_mask:0xf
	v_fmac_f32_dpp v161, v109, v45 row_newbcast:11 row_mask:0xf bank_mask:0xf
	v_fmac_f32_dpp v160, v110, v46 row_newbcast:11 row_mask:0xf bank_mask:0xf
	v_fmac_f32_dpp v161, v111, v47 row_newbcast:11 row_mask:0xf bank_mask:0xf
	v_fmac_f32_dpp v160, v108, v48 row_newbcast:12 row_mask:0xf bank_mask:0xf
	v_fmac_f32_dpp v161, v109, v49 row_newbcast:12 row_mask:0xf bank_mask:0xf
	v_fmac_f32_dpp v160, v110, v50 row_newbcast:12 row_mask:0xf bank_mask:0xf
	v_fmac_f32_dpp v161, v111, v51 row_newbcast:12 row_mask:0xf bank_mask:0xf
	v_fmac_f32_dpp v160, v108, v52 row_newbcast:13 row_mask:0xf bank_mask:0xf
	v_fmac_f32_dpp v161, v109, v53 row_newbcast:13 row_mask:0xf bank_mask:0xf
	v_fmac_f32_dpp v160, v110, v54 row_newbcast:13 row_mask:0xf bank_mask:0xf
	v_fmac_f32_dpp v161, v111, v55 row_newbcast:13 row_mask:0xf bank_mask:0xf
	v_fmac_f32_dpp v160, v108, v56 row_newbcast:14 row_mask:0xf bank_mask:0xf
	v_fmac_f32_dpp v161, v109, v57 row_newbcast:14 row_mask:0xf bank_mask:0xf
	v_fmac_f32_dpp v160, v110, v58 row_newbcast:14 row_mask:0xf bank_mask:0xf
	v_fmac_f32_dpp v161, v111, v59 row_newbcast:14 row_mask:0xf bank_mask:0xf
	v_fmac_f32_dpp v160, v108, v60 row_newbcast:15 row_mask:0xf bank_mask:0xf
	v_fmac_f32_dpp v161, v109, v61 row_newbcast:15 row_mask:0xf bank_mask:0xf
	v_fmac_f32_dpp v160, v110, v62 row_newbcast:15 row_mask:0xf bank_mask:0xf
	v_fmac_f32_dpp v161, v111, v63 row_newbcast:15 row_mask:0xf bank_mask:0xf
	v_add_f32_e32 v160, v160, v161
	buffer_store_dword v160, v167, s[68:71], s79 offen
	s_add_u32 s79, s79, 0x1000
	s_waitcnt vmcnt(0)
;     static __device__ __forceinline__ void dot(const float (&S)[64], const f32x4& a, float (&s)[4]) {
;         if constexpr (K == 0) {
;             asm volatile("v_mul_f32_dpp %0, %4, %8 row_newbcast:%16" DPPM "v_mul_f32_dpp %1, %5, %9 row_newbcast:%16" DPPM "v_mul_f32_dpp %2, %6, %10 row_newbcast:%16" DPPM "v_mul_f32_dpp %3, %7, %11 row_newbcast:%16" DPPM
;                          "v_fmac_f32_dpp %0, %4, %12 row_newbcast:%17" DPPM "v_fmac_f32_dpp %1, %5, %13 row_newbcast:%17" DPPM "v_fmac_f32_dpp %2, %6, %14 row_newbcast:%17" DPPM "v_fmac_f32_dpp %3, %7, %15 row_newbcast:%17" DPPM
;                          : "=&v"(s[0]), "=&v"(s[1]), "=&v"(s[2]), "=&v"(s[3])
;                          : "v"(a[0]), "v"(a[1]), "v"(a[2]), "v"(a[3]), "v"(S[K]), "v"(S[K + 1]), "v"(S[K + 2]), "v"(S[K + 3]), "v"(S[K + 4]), "v"(S[K + 5]), "v"(S[K + 6]), "v"(S[K + 7]), "n"(N0), "n"(N1));
;         } else
;         asm volatile("v_fmac_f32_dpp %0, %4, %8 row_newbcast:%16" DPPM "v_fmac_f32_dpp %1, %5, %9 row_newbcast:%16" DPPM "v_fmac_f32_dpp %2, %6, %10 row_newbcast:%16" DPPM "v_fmac_f32_dpp %3, %7, %11 row_newbcast:%16" DPPM
;                      "v_fmac_f32_dpp %0, %4, %12 row_newbcast:%17" DPPM "v_fmac_f32_dpp %1, %5, %13 row_newbcast:%17" DPPM "v_fmac_f32_dpp %2, %6, %14 row_newbcast:%17" DPPM "v_fmac_f32_dpp %3, %7, %15 row_newbcast:%17" DPPM
;                      : "+v"(s[0]), "+v"(s[1]), "+v"(s[2]), "+v"(s[3])
;                      : "v"(a[0]), "v"(a[1]), "v"(a[2]), "v"(a[3]), "v"(S[K]), "v"(S[K + 1]), "v"(S[K + 2]), "v"(S[K + 3]), "v"(S[K + 4]), "v"(S[K + 5]), "v"(S[K + 6]), "v"(S[K + 7]), "n"(N0), "n"(N1));
;         if constexpr (K + 8 < 64) ScanK<K + 8>::dot(S, a, s);
;     }
;     static __device__ __forceinline__ void upd(float (&S)[64], const In2& in, float sa, float vv, float& y0, float& y1) {
;         float t0, t1, t2, t3;
;         asm volatile("v_mul_f32_dpp %0, %10, %27 row_newbcast:%28" DPPM "v_mul_f32_dpp %1, %11, %27 row_newbcast:%28" DPPM "v_mul_f32_dpp %2, %12, %27 row_newbcast:%28" DPPM "v_mul_f32_dpp %3, %13, %27 row_newbcast:%28" DPPM
;                      "v_fmac_f32_dpp %0, %14, %6 row_newbcast:%28" DPPM "v_fmac_f32_dpp %1, %15, %7 row_newbcast:%28" DPPM "v_fmac_f32_dpp %2, %16, %8 row_newbcast:%28" DPPM "v_fmac_f32_dpp %3, %17, %9 row_newbcast:%28" DPPM
	buffer_load_dwordx4 v[96:99], v164, s[64:67], s72 offen
	buffer_load_dwordx4 v[100:103], v164, s[64:67], s73 offen
	buffer_load_dwordx4 v[104:107], v164, s[64:67], s74 offen
	buffer_load_dwordx4 v[108:111], v164, s[64:67], s75 offen
	buffer_load_dwordx2 v[112:113], v165, s[64:67], s76 offen
	buffer_load_ushort v114, v166, s[64:67], s77 offen
	s_cmp_lt_u32 s80, 255
	s_cselect_b32 s81, 0x1000, 0
	s_cselect_b32 s82, 0x800, 0
	s_cselect_b32 s9, 1, 0
	s_add_u32 s80, s80, s9
	s_add_u32 s72, s72, s81
	s_add_u32 s73, s73, s81
	s_add_u32 s74, s74, s81
	s_add_u32 s75, s75, s81
	s_add_u32 s78, s78, s81
	s_add_u32 s76, s76, s82
	s_add_u32 s77, s77, s82
	v_pk_fma_f32 v[144:145], v[124:125], v[148:149], v[152:153]
	v_pk_fma_f32 v[146:147], v[126:127], v[150:151], v[154:155]
	v_pk_mul_f32 v[136:137], v[120:121], v[124:125]
	v_pk_mul_f32 v[138:139], v[122:123], v[126:127]
	v_lshlrev_b32_e32 v140, 16, v132
	v_and_b32_e32 v141, 0xffff0000, v132
	v_lshlrev_b32_e32 v142, 16, v133
	v_and_b32_e32 v143, 0xffff0000, v133
	v_pk_mul_f32 v[140:141], v[140:141], v[144:145]
	v_pk_mul_f32 v[142:143], v[142:143], v[146:147]
	v_lshlrev_b32_e32 v163, 16, v134
	ds_write_b128 v168, v[136:139]
	ds_write_b128 v168, v[140:143] offset:256
	ds_read2_b32 v[64:65], v169 offset0:0 offset1:4
	ds_read2_b32 v[66:67], v169 offset0:8 offset1:12
	ds_read2_b32 v[68:69], v169 offset0:16 offset1:20
	ds_read2_b32 v[70:71], v169 offset0:24 offset1:28
	ds_read2_b32 v[72:73], v169 offset0:32 offset1:36
	ds_read2_b32 v[74:75], v169 offset0:40 offset1:44
	ds_read2_b32 v[76:77], v169 offset0:48 offset1:52
	ds_read2_b32 v[78:79], v169 offset0:56 offset1:60
	ds_read2_b32 v[80:81], v169 offset0:64 offset1:68
	ds_read2_b32 v[82:83], v169 offset0:72 offset1:76
	ds_read2_b32 v[84:85], v169 offset0:80 offset1:84
	ds_read2_b32 v[86:87], v169 offset0:88 offset1:92
	ds_read2_b32 v[88:89], v169 offset0:96 offset1:100
	ds_read2_b32 v[90:91], v169 offset0:104 offset1:108
	ds_read2_b32 v[92:93], v169 offset0:112 offset1:116
	ds_read2_b32 v[94:95], v169 offset0:120 offset1:124
	v_mul_f32_dpp v156, v120, v0 row_newbcast:0 row_mask:0xf bank_mask:0xf
	v_mul_f32_dpp v0, v116, v0 row_newbcast:0 row_mask:0xf bank_mask:0xf
	v_mul_f32_dpp v157, v121, v1 row_newbcast:0 row_mask:0xf bank_mask:0xf
	v_mul_f32_dpp v1, v117, v1 row_newbcast:0 row_mask:0xf bank_mask:0xf
	v_mul_f32_dpp v158, v122, v2 row_newbcast:0 row_mask:0xf bank_mask:0xf
	v_mul_f32_dpp v2, v118, v2 row_newbcast:0 row_mask:0xf bank_mask:0xf
	v_mul_f32_dpp v159, v123, v3 row_newbcast:0 row_mask:0xf bank_mask:0xf
	v_mul_f32_dpp v3, v119, v3 row_newbcast:0 row_mask:0xf bank_mask:0xf
	v_fmac_f32_dpp v156, v120, v4 row_newbcast:1 row_mask:0xf bank_mask:0xf
	v_mul_f32_dpp v4, v116, v4 row_newbcast:1 row_mask:0xf bank_mask:0xf
	v_fmac_f32_dpp v157, v121, v5 row_newbcast:1 row_mask:0xf bank_mask:0xf
	v_mul_f32_dpp v5, v117, v5 row_newbcast:1 row_mask:0xf bank_mask:0xf
	v_fmac_f32_dpp v158, v122, v6 row_newbcast:1 row_mask:0xf bank_mask:0xf
	v_mul_f32_dpp v6, v118, v6 row_newbcast:1 row_mask:0xf bank_mask:0xf
	v_fmac_f32_dpp v159, v123, v7 row_newbcast:1 row_mask:0xf bank_mask:0xf
	v_mul_f32_dpp v7, v119, v7 row_newbcast:1 row_mask:0xf bank_mask:0xf
	v_fmac_f32_dpp v156, v120, v8 row_newbcast:2 row_mask:0xf bank_mask:0xf
	v_mul_f32_dpp v8, v116, v8 row_newbcast:2 row_mask:0xf bank_mask:0xf
	v_fmac_f32_dpp v157, v121, v9 row_newbcast:2 row_mask:0xf bank_mask:0xf
	v_mul_f32_dpp v9, v117, v9 row_newbcast:2 row_mask:0xf bank_mask:0xf
	v_fmac_f32_dpp v158, v122, v10 row_newbcast:2 row_mask:0xf bank_mask:0xf
	v_mul_f32_dpp v10, v118, v10 row_newbcast:2 row_mask:0xf bank_mask:0xf
	v_fmac_f32_dpp v159, v123, v11 row_newbcast:2 row_mask:0xf bank_mask:0xf
	v_mul_f32_dpp v11, v119, v11 row_newbcast:2 row_mask:0xf bank_mask:0xf
	v_fmac_f32_dpp v156, v120, v12 row_newbcast:3 row_mask:0xf bank_mask:0xf
	v_mul_f32_dpp v12, v116, v12 row_newbcast:3 row_mask:0xf bank_mask:0xf
	v_fmac_f32_dpp v157, v121, v13 row_newbcast:3 row_mask:0xf bank_mask:0xf
	v_mul_f32_dpp v13, v117, v13 row_newbcast:3 row_mask:0xf bank_mask:0xf
	v_fmac_f32_dpp v158, v122, v14 row_newbcast:3 row_mask:0xf bank_mask:0xf
	v_mul_f32_dpp v14, v118, v14 row_newbcast:3 row_mask:0xf bank_mask:0xf
	v_fmac_f32_dpp v159, v123, v15 row_newbcast:3 row_mask:0xf bank_mask:0xf
	v_mul_f32_dpp v15, v119, v15 row_newbcast:3 row_mask:0xf bank_mask:0xf
	v_fmac_f32_dpp v156, v120, v16 row_newbcast:4 row_mask:0xf bank_mask:0xf
	v_mul_f32_dpp v16, v116, v16 row_newbcast:4 row_mask:0xf bank_mask:0xf
	v_fmac_f32_dpp v157, v121, v17 row_newbcast:4 row_mask:0xf bank_mask:0xf
	v_mul_f32_dpp v17, v117, v17 row_newbcast:4 row_mask:0xf bank_mask:0xf
	v_fmac_f32_dpp v158, v122, v18 row_newbcast:4 row_mask:0xf bank_mask:0xf
	v_mul_f32_dpp v18, v118, v18 row_newbcast:4 row_mask:0xf bank_mask:0xf
	v_fmac_f32_dpp v159, v123, v19 row_newbcast:4 row_mask:0xf bank_mask:0xf
	v_mul_f32_dpp v19, v119, v19 row_newbcast:4 row_mask:0xf bank_mask:0xf
	v_fmac_f32_dpp v156, v120, v20 row_newbcast:5 row_mask:0xf bank_mask:0xf
	v_mul_f32_dpp v20, v116, v20 row_newbcast:5 row_mask:0xf bank_mask:0xf
	v_fmac_f32_dpp v157, v121, v21 row_newbcast:5 row_mask:0xf bank_mask:0xf
	v_mul_f32_dpp v21, v117, v21 row_newbcast:5 row_mask:0xf bank_mask:0xf
	v_fmac_f32_dpp v158, v122, v22 row_newbcast:5 row_mask:0xf bank_mask:0xf
	v_mul_f32_dpp v22, v118, v22 row_newbcast:5 row_mask:0xf bank_mask:0xf
	v_fmac_f32_dpp v159, v123, v23 row_newbcast:5 row_mask:0xf bank_mask:0xf
	v_mul_f32_dpp v23, v119, v23 row_newbcast:5 row_mask:0xf bank_mask:0xf
	v_fmac_f32_dpp v156, v120, v24 row_newbcast:6 row_mask:0xf bank_mask:0xf
	v_mul_f32_dpp v24, v116, v24 row_newbcast:6 row_mask:0xf bank_mask:0xf
;     static __device__ __forceinline__ void dot(const float (&S)[64], const f32x4& a, float (&s)[4]) {
;         if constexpr (K == 0) {
;             asm volatile("v_mul_f32_dpp %0, %4, %8 row_newbcast:%16" DPPM "v_mul_f32_dpp %1, %5, %9 row_newbcast:%16" DPPM "v_mul_f32_dpp %2, %6, %10 row_newbcast:%16" DPPM "v_mul_f32_dpp %3, %7, %11 row_newbcast:%16" DPPM
;                          "v_fmac_f32_dpp %0, %4, %12 row_newbcast:%17" DPPM "v_fmac_f32_dpp %1, %5, %13 row_newbcast:%17" DPPM "v_fmac_f32_dpp %2, %6, %14 row_newbcast:%17" DPPM "v_fmac_f32_dpp %3, %7, %15 row_newbcast:%17" DPPM
;                          : "=&v"(s[0]), "=&v"(s[1]), "=&v"(s[2]), "=&v"(s[3])
;                          : "v"(a[0]), "v"(a[1]), "v"(a[2]), "v"(a[3]), "v"(S[K]), "v"(S[K + 1]), "v"(S[K + 2]), "v"(S[K + 3]), "v"(S[K + 4]), "v"(S[K + 5]), "v"(S[K + 6]), "v"(S[K + 7]), "n"(N0), "n"(N1));
;         } else
;         asm volatile("v_fmac_f32_dpp %0, %4, %8 row_newbcast:%16" DPPM "v_fmac_f32_dpp %1, %5, %9 row_newbcast:%16" DPPM "v_fmac_f32_dpp %2, %6, %10 row_newbcast:%16" DPPM "v_fmac_f32_dpp %3, %7, %11 row_newbcast:%16" DPPM
;                      "v_fmac_f32_dpp %0, %4, %12 row_newbcast:%17" DPPM "v_fmac_f32_dpp %1, %5, %13 row_newbcast:%17" DPPM "v_fmac_f32_dpp %2, %6, %14 row_newbcast:%17" DPPM "v_fmac_f32_dpp %3, %7, %15 row_newbcast:%17" DPPM
;                      : "+v"(s[0]), "+v"(s[1]), "+v"(s[2]), "+v"(s[3])
;                      : "v"(a[0]), "v"(a[1]), "v"(a[2]), "v"(a[3]), "v"(S[K]), "v"(S[K + 1]), "v"(S[K + 2]), "v"(S[K + 3]), "v"(S[K + 4]), "v"(S[K + 5]), "v"(S[K + 6]), "v"(S[K + 7]), "n"(N0), "n"(N1));
;         if constexpr (K + 8 < 64) ScanK<K + 8>::dot(S, a, s);
;     }
	v_fmac_f32_dpp v157, v121, v25 row_newbcast:6 row_mask:0xf bank_mask:0xf
	v_mul_f32_dpp v25, v117, v25 row_newbcast:6 row_mask:0xf bank_mask:0xf
	v_fmac_f32_dpp v158, v122, v26 row_newbcast:6 row_mask:0xf bank_mask:0xf
	v_mul_f32_dpp v26, v118, v26 row_newbcast:6 row_mask:0xf bank_mask:0xf
	v_fmac_f32_dpp v159, v123, v27 row_newbcast:6 row_mask:0xf bank_mask:0xf
	v_mul_f32_dpp v27, v119, v27 row_newbcast:6 row_mask:0xf bank_mask:0xf
	v_fmac_f32_dpp v156, v120, v28 row_newbcast:7 row_mask:0xf bank_mask:0xf
	v_mul_f32_dpp v28, v116, v28 row_newbcast:7 row_mask:0xf bank_mask:0xf
	v_fmac_f32_dpp v157, v121, v29 row_newbcast:7 row_mask:0xf bank_mask:0xf
	v_mul_f32_dpp v29, v117, v29 row_newbcast:7 row_mask:0xf bank_mask:0xf
	v_fmac_f32_dpp v158, v122, v30 row_newbcast:7 row_mask:0xf bank_mask:0xf
	v_mul_f32_dpp v30, v118, v30 row_newbcast:7 row_mask:0xf bank_mask:0xf
	v_fmac_f32_dpp v159, v123, v31 row_newbcast:7 row_mask:0xf bank_mask:0xf
	v_mul_f32_dpp v31, v119, v31 row_newbcast:7 row_mask:0xf bank_mask:0xf
	v_fmac_f32_dpp v156, v120, v32 row_newbcast:8 row_mask:0xf bank_mask:0xf
	v_mul_f32_dpp v32, v116, v32 row_newbcast:8 row_mask:0xf bank_mask:0xf
	v_fmac_f32_dpp v157, v121, v33 row_newbcast:8 row_mask:0xf bank_mask:0xf
	v_mul_f32_dpp v33, v117, v33 row_newbcast:8 row_mask:0xf bank_mask:0xf
	v_fmac_f32_dpp v158, v122, v34 row_newbcast:8 row_mask:0xf bank_mask:0xf
	v_mul_f32_dpp v34, v118, v34 row_newbcast:8 row_mask:0xf bank_mask:0xf
	v_fmac_f32_dpp v159, v123, v35 row_newbcast:8 row_mask:0xf bank_mask:0xf
	v_mul_f32_dpp v35, v119, v35 row_newbcast:8 row_mask:0xf bank_mask:0xf
	v_fmac_f32_dpp v156, v120, v36 row_newbcast:9 row_mask:0xf bank_mask:0xf
	v_mul_f32_dpp v36, v116, v36 row_newbcast:9 row_mask:0xf bank_mask:0xf
	v_fmac_f32_dpp v157, v121, v37 row_newbcast:9 row_mask:0xf bank_mask:0xf
	v_mul_f32_dpp v37, v117, v37 row_newbcast:9 row_mask:0xf bank_mask:0xf
	v_fmac_f32_dpp v158, v122, v38 row_newbcast:9 row_mask:0xf bank_mask:0xf
	v_mul_f32_dpp v38, v118, v38 row_newbcast:9 row_mask:0xf bank_mask:0xf
	v_fmac_f32_dpp v159, v123, v39 row_newbcast:9 row_mask:0xf bank_mask:0xf
	v_mul_f32_dpp v39, v119, v39 row_newbcast:9 row_mask:0xf bank_mask:0xf
	v_fmac_f32_dpp v156, v120, v40 row_newbcast:10 row_mask:0xf bank_mask:0xf
	v_mul_f32_dpp v40, v116, v40 row_newbcast:10 row_mask:0xf bank_mask:0xf
	v_fmac_f32_dpp v157, v121, v41 row_newbcast:10 row_mask:0xf bank_mask:0xf
	v_mul_f32_dpp v41, v117, v41 row_newbcast:10 row_mask:0xf bank_mask:0xf
	v_fmac_f32_dpp v158, v122, v42 row_newbcast:10 row_mask:0xf bank_mask:0xf
	v_mul_f32_dpp v42, v118, v42 row_newbcast:10 row_mask:0xf bank_mask:0xf
	v_fmac_f32_dpp v159, v123, v43 row_newbcast:10 row_mask:0xf bank_mask:0xf
	v_mul_f32_dpp v43, v119, v43 row_newbcast:10 row_mask:0xf bank_mask:0xf
	v_fmac_f32_dpp v156, v120, v44 row_newbcast:11 row_mask:0xf bank_mask:0xf
	v_mul_f32_dpp v44, v116, v44 row_newbcast:11 row_mask:0xf bank_mask:0xf
	v_fmac_f32_dpp v157, v121, v45 row_newbcast:11 row_mask:0xf bank_mask:0xf
	v_mul_f32_dpp v45, v117, v45 row_newbcast:11 row_mask:0xf bank_mask:0xf
	v_fmac_f32_dpp v158, v122, v46 row_newbcast:11 row_mask:0xf bank_mask:0xf
	v_mul_f32_dpp v46, v118, v46 row_newbcast:11 row_mask:0xf bank_mask:0xf
	v_fmac_f32_dpp v159, v123, v47 row_newbcast:11 row_mask:0xf bank_mask:0xf
	v_mul_f32_dpp v47, v119, v47 row_newbcast:11 row_mask:0xf bank_mask:0xf
	v_fmac_f32_dpp v156, v120, v48 row_newbcast:12 row_mask:0xf bank_mask:0xf
	v_mul_f32_dpp v48, v116, v48 row_newbcast:12 row_mask:0xf bank_mask:0xf
	v_fmac_f32_dpp v157, v121, v49 row_newbcast:12 row_mask:0xf bank_mask:0xf
	v_mul_f32_dpp v49, v117, v49 row_newbcast:12 row_mask:0xf bank_mask:0xf
	v_fmac_f32_dpp v158, v122, v50 row_newbcast:12 row_mask:0xf bank_mask:0xf
	v_mul_f32_dpp v50, v118, v50 row_newbcast:12 row_mask:0xf bank_mask:0xf
	v_fmac_f32_dpp v159, v123, v51 row_newbcast:12 row_mask:0xf bank_mask:0xf
	v_mul_f32_dpp v51, v119, v51 row_newbcast:12 row_mask:0xf bank_mask:0xf
	v_fmac_f32_dpp v156, v120, v52 row_newbcast:13 row_mask:0xf bank_mask:0xf
	v_mul_f32_dpp v52, v116, v52 row_newbcast:13 row_mask:0xf bank_mask:0xf
	v_fmac_f32_dpp v157, v121, v53 row_newbcast:13 row_mask:0xf bank_mask:0xf
	v_mul_f32_dpp v53, v117, v53 row_newbcast:13 row_mask:0xf bank_mask:0xf
	v_fmac_f32_dpp v158, v122, v54 row_newbcast:13 row_mask:0xf bank_mask:0xf
	v_mul_f32_dpp v54, v118, v54 row_newbcast:13 row_mask:0xf bank_mask:0xf
	v_fmac_f32_dpp v159, v123, v55 row_newbcast:13 row_mask:0xf bank_mask:0xf
	v_mul_f32_dpp v55, v119, v55 row_newbcast:13 row_mask:0xf bank_mask:0xf
	v_fmac_f32_dpp v156, v120, v56 row_newbcast:14 row_mask:0xf bank_mask:0xf
	v_mul_f32_dpp v56, v116, v56 row_newbcast:14 row_mask:0xf bank_mask:0xf
	v_fmac_f32_dpp v157, v121, v57 row_newbcast:14 row_mask:0xf bank_mask:0xf
	v_mul_f32_dpp v57, v117, v57 row_newbcast:14 row_mask:0xf bank_mask:0xf
	v_fmac_f32_dpp v158, v122, v58 row_newbcast:14 row_mask:0xf bank_mask:0xf
	v_mul_f32_dpp v58, v118, v58 row_newbcast:14 row_mask:0xf bank_mask:0xf
	v_fmac_f32_dpp v159, v123, v59 row_newbcast:14 row_mask:0xf bank_mask:0xf
	v_mul_f32_dpp v59, v119, v59 row_newbcast:14 row_mask:0xf bank_mask:0xf
	v_fmac_f32_dpp v156, v120, v60 row_newbcast:15 row_mask:0xf bank_mask:0xf
	v_mul_f32_dpp v60, v116, v60 row_newbcast:15 row_mask:0xf bank_mask:0xf
	v_fmac_f32_dpp v157, v121, v61 row_newbcast:15 row_mask:0xf bank_mask:0xf
	v_mul_f32_dpp v61, v117, v61 row_newbcast:15 row_mask:0xf bank_mask:0xf
	v_fmac_f32_dpp v158, v122, v62 row_newbcast:15 row_mask:0xf bank_mask:0xf
	v_mul_f32_dpp v62, v118, v62 row_newbcast:15 row_mask:0xf bank_mask:0xf
	v_fmac_f32_dpp v159, v123, v63 row_newbcast:15 row_mask:0xf bank_mask:0xf
	v_mul_f32_dpp v63, v119, v63 row_newbcast:15 row_mask:0xf bank_mask:0xf
	v_add_f32_e32 v156, v156, v157
	v_add_f32_e32 v158, v158, v159
	v_add_f32_e32 v156, v156, v158
	v_xor_b32_e32 v162, 0x80000000, v156
	s_waitcnt lgkmcnt(0)
; #define SB __builtin_amdgcn_sched_barrier(0)
; #define ST2(set, s) { DERIVE_BK(set); float sd[4]; ScanK<0>::dot(S, set.a, sd); float y0 = set.yo, y1 = 0.f; ScanK<0>::upd(S, set, -((sd[0] + sd[1]) + (sd[2] + sd[3])), __uint_as_float(set.v << 16), y0, y1); __builtin_amdgcn_raw_buffer_store_b32(__float_as_uint(y0 + y1), rY, lo4b, ob4 + (unsigned)((int)(s) * (int)stp * 4), 0); }
;     static __device__ __forceinline__ void upd(float (&S)[64], const In2& in, float sa, float vv, float& y0, float& y1) {
;         float t0, t1, t2, t3;
;         asm volatile("v_mul_f32_dpp %0, %10, %27 row_newbcast:%28" DPPM "v_mul_f32_dpp %1, %11, %27 row_newbcast:%28" DPPM "v_mul_f32_dpp %2, %12, %27 row_newbcast:%28" DPPM "v_mul_f32_dpp %3, %13, %27 row_newbcast:%28" DPPM
;                      "v_fmac_f32_dpp %0, %14, %6 row_newbcast:%28" DPPM "v_fmac_f32_dpp %1, %15, %7 row_newbcast:%28" DPPM "v_fmac_f32_dpp %2, %16, %8 row_newbcast:%28" DPPM "v_fmac_f32_dpp %3, %17, %9 row_newbcast:%28" DPPM
;                      "v_fmac_f32_dpp %0, %18, %26 row_newbcast:%28" DPPM "v_fmac_f32_dpp %1, %19, %26 row_newbcast:%28" DPPM "v_fmac_f32_dpp %2, %20, %26 row_newbcast:%28" DPPM "v_fmac_f32_dpp %3, %21, %26 row_newbcast:%28" DPPM
;                      "v_fmac_f32_dpp %4, %22, %0 row_newbcast:%28" DPPM "v_fmac_f32_dpp %5, %23, %1 row_newbcast:%28" DPPM "v_fmac_f32_dpp %4, %24, %2 row_newbcast:%28" DPPM "v_fmac_f32_dpp %5, %25, %3 row_newbcast:%28" DPPM
;                      : "=&v"(t0), "=&v"(t1), "=&v"(t2), "=&v"(t3), "+v"(y0), "+v"(y1)
;                      : "v"(S[K]), "v"(S[K + 1]), "v"(S[K + 2]), "v"(S[K + 3]), "v"(in.kd[0]), "v"(in.kd[1]), "v"(in.kd[2]), "v"(in.kd[3]), "v"(in.w[0]), "v"(in.w[1]), "v"(in.w[2]), "v"(in.w[3]),
;                        "v"(in.b[0]), "v"(in.b[1]), "v"(in.b[2]), "v"(in.b[3]), "v"(in.r[0]), "v"(in.r[1]), "v"(in.r[2]), "v"(in.r[3]), "v"(sa), "v"(vv), "n"(N0));
;         S[K] = t0; S[K + 1] = t1; S[K + 2] = t2; S[K + 3] = t3;
;         if constexpr (K + 4 < 64) ScanK<K + 4>::upd(S, in, sa, vv, y0, y1);
; __device__ __forceinline__ void scan_pass2(const Params& p, int d) {
;     ...
;         In2 i0, i1; LD2(i0, 0);
; #pragma unroll 1
;         for (int s = 0; s < LC; s += 2) { TOUCH2(i0); SB; LD2(i1, s + 1); SB; ST2(i0, s); TOUCH2(i1); SB; LD2(i0, s + 2); SB; ST2(i1, s + 1); }
	s_nop 1
	v_mfma_f32_4x4x1_16b_f32 v[0:3], v64, v162, v[0:3]
	v_mfma_f32_4x4x1_16b_f32 v[4:7], v65, v162, v[4:7]
	v_mfma_f32_4x4x1_16b_f32 v[8:11], v66, v162, v[8:11]
	v_mfma_f32_4x4x1_16b_f32 v[12:15], v67, v162, v[12:15]
	v_mfma_f32_4x4x1_16b_f32 v[16:19], v68, v162, v[16:19]
	v_mfma_f32_4x4x1_16b_f32 v[20:23], v69, v162, v[20:23]
	v_mfma_f32_4x4x1_16b_f32 v[24:27], v70, v162, v[24:27]
	v_mfma_f32_4x4x1_16b_f32 v[28:31], v71, v162, v[28:31]
	v_mfma_f32_4x4x1_16b_f32 v[32:35], v72, v162, v[32:35]
	v_mfma_f32_4x4x1_16b_f32 v[36:39], v73, v162, v[36:39]
	v_mfma_f32_4x4x1_16b_f32 v[40:43], v74, v162, v[40:43]
	v_mfma_f32_4x4x1_16b_f32 v[44:47], v75, v162, v[44:47]
	v_mfma_f32_4x4x1_16b_f32 v[48:51], v76, v162, v[48:51]
	v_mfma_f32_4x4x1_16b_f32 v[52:55], v77, v162, v[52:55]
	v_mfma_f32_4x4x1_16b_f32 v[56:59], v78, v162, v[56:59]
	v_mfma_f32_4x4x1_16b_f32 v[60:63], v79, v162, v[60:63]
	v_mfma_f32_4x4x1_16b_f32 v[0:3], v80, v163, v[0:3]
	v_mfma_f32_4x4x1_16b_f32 v[4:7], v81, v163, v[4:7]
	v_mfma_f32_4x4x1_16b_f32 v[8:11], v82, v163, v[8:11]
	v_mfma_f32_4x4x1_16b_f32 v[12:15], v83, v163, v[12:15]
	v_mfma_f32_4x4x1_16b_f32 v[16:19], v84, v163, v[16:19]
	v_mfma_f32_4x4x1_16b_f32 v[20:23], v85, v163, v[20:23]
	v_mfma_f32_4x4x1_16b_f32 v[24:27], v86, v163, v[24:27]
	v_mfma_f32_4x4x1_16b_f32 v[28:31], v87, v163, v[28:31]
	v_mfma_f32_4x4x1_16b_f32 v[32:35], v88, v163, v[32:35]
	v_mfma_f32_4x4x1_16b_f32 v[36:39], v89, v163, v[36:39]
	v_mfma_f32_4x4x1_16b_f32 v[40:43], v90, v163, v[40:43]
	v_mfma_f32_4x4x1_16b_f32 v[44:47], v91, v163, v[44:47]
	v_mfma_f32_4x4x1_16b_f32 v[48:51], v92, v163, v[48:51]
	v_mfma_f32_4x4x1_16b_f32 v[52:55], v93, v163, v[52:55]
	v_mfma_f32_4x4x1_16b_f32 v[56:59], v94, v163, v[56:59]
	v_mfma_f32_4x4x1_16b_f32 v[60:63], v95, v163, v[60:63]
	v_mul_f32_dpp v160, v128, v0 row_newbcast:0 row_mask:0xf bank_mask:0xf
	v_mul_f32_dpp v161, v129, v1 row_newbcast:0 row_mask:0xf bank_mask:0xf
	v_fmac_f32_dpp v160, v130, v2 row_newbcast:0 row_mask:0xf bank_mask:0xf
	v_fmac_f32_dpp v161, v131, v3 row_newbcast:0 row_mask:0xf bank_mask:0xf
	v_fmac_f32_dpp v160, v128, v4 row_newbcast:1 row_mask:0xf bank_mask:0xf
	v_fmac_f32_dpp v161, v129, v5 row_newbcast:1 row_mask:0xf bank_mask:0xf
	v_fmac_f32_dpp v160, v130, v6 row_newbcast:1 row_mask:0xf bank_mask:0xf
	v_fmac_f32_dpp v161, v131, v7 row_newbcast:1 row_mask:0xf bank_mask:0xf
	v_fmac_f32_dpp v160, v128, v8 row_newbcast:2 row_mask:0xf bank_mask:0xf
	v_fmac_f32_dpp v161, v129, v9 row_newbcast:2 row_mask:0xf bank_mask:0xf
	v_fmac_f32_dpp v160, v130, v10 row_newbcast:2 row_mask:0xf bank_mask:0xf
	v_fmac_f32_dpp v161, v131, v11 row_newbcast:2 row_mask:0xf bank_mask:0xf
	v_fmac_f32_dpp v160, v128, v12 row_newbcast:3 row_mask:0xf bank_mask:0xf
	v_fmac_f32_dpp v161, v129, v13 row_newbcast:3 row_mask:0xf bank_mask:0xf
	v_fmac_f32_dpp v160, v130, v14 row_newbcast:3 row_mask:0xf bank_mask:0xf
	v_fmac_f32_dpp v161, v131, v15 row_newbcast:3 row_mask:0xf bank_mask:0xf
	v_fmac_f32_dpp v160, v128, v16 row_newbcast:4 row_mask:0xf bank_mask:0xf
	v_fmac_f32_dpp v161, v129, v17 row_newbcast:4 row_mask:0xf bank_mask:0xf
	v_fmac_f32_dpp v160, v130, v18 row_newbcast:4 row_mask:0xf bank_mask:0xf
	v_fmac_f32_dpp v161, v131, v19 row_newbcast:4 row_mask:0xf bank_mask:0xf
	v_fmac_f32_dpp v160, v128, v20 row_newbcast:5 row_mask:0xf bank_mask:0xf
	v_fmac_f32_dpp v161, v129, v21 row_newbcast:5 row_mask:0xf bank_mask:0xf
	v_fmac_f32_dpp v160, v130, v22 row_newbcast:5 row_mask:0xf bank_mask:0xf
	v_fmac_f32_dpp v161, v131, v23 row_newbcast:5 row_mask:0xf bank_mask:0xf
	v_fmac_f32_dpp v160, v128, v24 row_newbcast:6 row_mask:0xf bank_mask:0xf
	v_fmac_f32_dpp v161, v129, v25 row_newbcast:6 row_mask:0xf bank_mask:0xf
	v_fmac_f32_dpp v160, v130, v26 row_newbcast:6 row_mask:0xf bank_mask:0xf
	v_fmac_f32_dpp v161, v131, v27 row_newbcast:6 row_mask:0xf bank_mask:0xf
	v_fmac_f32_dpp v160, v128, v28 row_newbcast:7 row_mask:0xf bank_mask:0xf
	v_fmac_f32_dpp v161, v129, v29 row_newbcast:7 row_mask:0xf bank_mask:0xf
	v_fmac_f32_dpp v160, v130, v30 row_newbcast:7 row_mask:0xf bank_mask:0xf
	v_fmac_f32_dpp v161, v131, v31 row_newbcast:7 row_mask:0xf bank_mask:0xf
	v_fmac_f32_dpp v160, v128, v32 row_newbcast:8 row_mask:0xf bank_mask:0xf
	v_fmac_f32_dpp v161, v129, v33 row_newbcast:8 row_mask:0xf bank_mask:0xf
	v_fmac_f32_dpp v160, v130, v34 row_newbcast:8 row_mask:0xf bank_mask:0xf
	v_fmac_f32_dpp v161, v131, v35 row_newbcast:8 row_mask:0xf bank_mask:0xf
	v_fmac_f32_dpp v160, v128, v36 row_newbcast:9 row_mask:0xf bank_mask:0xf
	v_fmac_f32_dpp v161, v129, v37 row_newbcast:9 row_mask:0xf bank_mask:0xf
	v_fmac_f32_dpp v160, v130, v38 row_newbcast:9 row_mask:0xf bank_mask:0xf
	v_fmac_f32_dpp v161, v131, v39 row_newbcast:9 row_mask:0xf bank_mask:0xf
	v_fmac_f32_dpp v160, v128, v40 row_newbcast:10 row_mask:0xf bank_mask:0xf
	v_fmac_f32_dpp v161, v129, v41 row_newbcast:10 row_mask:0xf bank_mask:0xf
	v_fmac_f32_dpp v160, v130, v42 row_newbcast:10 row_mask:0xf bank_mask:0xf
	v_fmac_f32_dpp v161, v131, v43 row_newbcast:10 row_mask:0xf bank_mask:0xf
	v_fmac_f32_dpp v160, v128, v44 row_newbcast:11 row_mask:0xf bank_mask:0xf
	v_fmac_f32_dpp v161, v129, v45 row_newbcast:11 row_mask:0xf bank_mask:0xf
	v_fmac_f32_dpp v160, v130, v46 row_newbcast:11 row_mask:0xf bank_mask:0xf
	v_fmac_f32_dpp v161, v131, v47 row_newbcast:11 row_mask:0xf bank_mask:0xf
	v_fmac_f32_dpp v160, v128, v48 row_newbcast:12 row_mask:0xf bank_mask:0xf
	v_fmac_f32_dpp v161, v129, v49 row_newbcast:12 row_mask:0xf bank_mask:0xf
	v_fmac_f32_dpp v160, v130, v50 row_newbcast:12 row_mask:0xf bank_mask:0xf
	v_fmac_f32_dpp v161, v131, v51 row_newbcast:12 row_mask:0xf bank_mask:0xf
	v_fmac_f32_dpp v160, v128, v52 row_newbcast:13 row_mask:0xf bank_mask:0xf
	v_fmac_f32_dpp v161, v129, v53 row_newbcast:13 row_mask:0xf bank_mask:0xf
	v_fmac_f32_dpp v160, v130, v54 row_newbcast:13 row_mask:0xf bank_mask:0xf
	v_fmac_f32_dpp v161, v131, v55 row_newbcast:13 row_mask:0xf bank_mask:0xf
	v_fmac_f32_dpp v160, v128, v56 row_newbcast:14 row_mask:0xf bank_mask:0xf
	v_fmac_f32_dpp v161, v129, v57 row_newbcast:14 row_mask:0xf bank_mask:0xf
	v_fmac_f32_dpp v160, v130, v58 row_newbcast:14 row_mask:0xf bank_mask:0xf
	v_fmac_f32_dpp v161, v131, v59 row_newbcast:14 row_mask:0xf bank_mask:0xf
	v_fmac_f32_dpp v160, v128, v60 row_newbcast:15 row_mask:0xf bank_mask:0xf
	v_fmac_f32_dpp v161, v129, v61 row_newbcast:15 row_mask:0xf bank_mask:0xf
	v_fmac_f32_dpp v160, v130, v62 row_newbcast:15 row_mask:0xf bank_mask:0xf
	v_fmac_f32_dpp v161, v131, v63 row_newbcast:15 row_mask:0xf bank_mask:0xf
	v_add_f32_e32 v160, v160, v161
	buffer_store_dword v160, v167, s[68:71], s79 offen
	s_add_u32 s79, s79, 0x1000
	s_sub_u32 s83, s83, 1
	s_cmp_lg_u32 s83, 0
	s_cbranch_scc1 .Lmy_p2d0_loop
	s_lshl_b32 s6, s96, 3
	s_add_i32 s0, s0, s6
	s_branch .Lmy_p2d0_item
